# lane reductions without LDS crossbar round trips: combine 16-lane sum via 4 DPP adds (bit-identical); P1/P10/final 64-lane sums via 4 DPP adds + permlane16/32 swaps
# speedup vs baseline: 1.0019x; 1.0019x over previous
.LBB0_53:
	s_or_b64 exec, exec, s[14:15]
	v_lshlrev_b64 v[0:1], v22, v[0:1]
	v_lshl_add_u64 v[0:1], v[20:21], 0, v[0:1]
	v_lshlrev_b64 v[2:3], 12, v[2:3]
	v_lshl_add_u64 v[0:1], v[0:1], 0, v[2:3]
	v_lshl_add_u64 v[42:43], v[0:1], 0, v[8:9]
	global_load_dwordx4 v[20:23], v[42:43], off nt
	global_load_dwordx4 v[34:37], v[42:43], off offset:1024 nt
	global_load_dwordx4 v[38:41], v[42:43], off offset:2048 nt
	global_load_dwordx4 v[0:3], v[42:43], off offset:3072 nt
	v_lshl_add_u64 v[18:19], s[28:29], 0, v[18:19]
	v_lshl_add_u64 v[54:55], v[18:19], 0, s[12:13]
	v_lshl_add_u64 v[50:51], v[54:55], 0, v[8:9]
	global_load_dwordx4 v[42:45], v[50:51], off
	v_lshl_add_u64 v[56:57], v[18:19], 0, v[8:9]
	global_load_dwordx4 v[50:53], v[56:57], off
	v_lshl_add_u64 v[112:113], v[54:55], 0, v[12:13]
	global_load_dwordx4 v[88:91], v[112:113], off
	global_load_dwordx4 v[100:103], v[56:57], off offset:1024
	v_lshl_add_u64 v[114:115], v[54:55], 0, v[14:15]
	global_load_dwordx4 v[92:95], v[114:115], off
	global_load_dwordx4 v[104:107], v[56:57], off offset:2048
	v_lshl_add_u64 v[116:117], v[54:55], 0, v[16:17]
	global_load_dwordx4 v[96:99], v[116:117], off
	global_load_dwordx4 v[108:111], v[56:57], off offset:3072
	s_waitcnt vmcnt(11)
	v_mov_b32_e32 v58, v21
	s_waitcnt vmcnt(10)
	v_mov_b32_e32 v59, v35
	v_mov_b32_e32 v18, v20
	v_mov_b32_e32 v19, v34
	s_waitcnt vmcnt(9)
	v_mov_b32_e32 v66, v39
	s_waitcnt vmcnt(8)
	v_mov_b32_e32 v67, v1
	v_pk_mul_f32 v[58:59], v[58:59], v[58:59]
	v_mov_b32_e32 v60, v22
	v_mov_b32_e32 v61, v36
	v_mov_b32_e32 v64, v38
	v_mov_b32_e32 v65, v0
	v_pk_mul_f32 v[66:67], v[66:67], v[66:67]
	v_pk_fma_f32 v[18:19], v[18:19], v[18:19], v[58:59]
	v_mov_b32_e32 v62, v23
	v_mov_b32_e32 v63, v37
	v_mov_b32_e32 v68, v40
	v_mov_b32_e32 v69, v2
	v_pk_fma_f32 v[58:59], v[64:65], v[64:65], v[66:67]
	v_pk_fma_f32 v[18:19], v[60:61], v[60:61], v[18:19]
	v_mov_b32_e32 v70, v41
	v_mov_b32_e32 v71, v3
	v_pk_fma_f32 v[58:59], v[68:69], v[68:69], v[58:59]
	v_pk_fma_f32 v[18:19], v[62:63], v[62:63], v[18:19]
	v_pk_fma_f32 v[58:59], v[70:71], v[70:71], v[58:59]
	v_add_f32_e32 v4, v18, v19
	v_add_f32_e32 v4, v4, v58
	v_add_f32_e32 v4, v4, v59
	v_ashrrev_i32_e32 v18, 13, v32
	v_add_u32_e32 v18, v18, v33
	v_add_f32_dpp v4, v4, v4 quad_perm:[1,0,3,2] row_mask:0xf bank_mask:0xf
	v_ashrrev_i32_e32 v19, 31, v18
	v_mul_i32_i24_e32 v58, 0x4400, v18
	v_add_f32_dpp v4, v4, v4 quad_perm:[2,3,0,1] row_mask:0xf bank_mask:0xf
	v_sub_u32_e32 v58, v24, v58
	v_lshlrev_b64 v[18:19], 26, v[18:19]
	v_add_f32_dpp v4, v4, v4 row_half_mirror row_mask:0xf bank_mask:0xf
	v_lshl_add_u64 v[18:19], s[74:75], 0, v[18:19]
	v_ashrrev_i32_e32 v59, 31, v58
	v_add_f32_dpp v4, v4, v4 row_mirror row_mask:0xf bank_mask:0xf
	v_mov_b32_e32 v126, v4
	v_mov_b32_e32 v127, v4
	v_lshlrev_b64 v[58:59], 11, v[58:59]
	v_lshl_add_u64 v[18:19], v[18:19], 0, v[58:59]
	v_permlane16_swap_b32 v126, v127
	v_add_u32_e32 v24, s6, v24
	s_nop 0
	v_add_f32_e32 v4, v126, v127
	v_mov_b32_e32 v126, v4
	v_mov_b32_e32 v127, v4
	s_nop 1
	v_permlane32_swap_b32 v126, v127
	s_nop 1
	v_add_f32_e32 v4, v126, v127
	v_fmamk_f32 v4, v4, 0x3a800000, v31
	v_mul_f32_e32 v58, 0x4b800000, v4
	v_cmp_gt_f32_e32 vcc, s11, v4
	s_nop 1
	v_cndmask_b32_e32 v4, v4, v58, vcc
	v_rsq_f32_e32 v4, v4
	v_lshl_add_u64 v[58:59], v[18:19], 0, v[10:11]
	s_waitcnt vmcnt(0)
	v_pk_add_f32 v[18:19], v[42:43], 1.0 op_sel_hi:[1,0]
	v_pk_add_f32 v[42:43], v[44:45], 1.0 op_sel_hi:[1,0]
	v_mul_f32_e32 v44, 0x45800000, v4
	v_cndmask_b32_e32 v4, v4, v44, vcc
	v_pk_mul_f32 v[20:21], v[20:21], v[4:5] op_sel_hi:[1,0]
	v_pk_mul_f32 v[22:23], v[22:23], v[4:5] op_sel_hi:[1,0]
	v_pk_mul_f32 v[32:33], v[34:35], v[4:5] op_sel_hi:[1,0]
	v_pk_mul_f32 v[34:35], v[36:37], v[4:5] op_sel_hi:[1,0]
	v_pk_mul_f32 v[20:21], v[72:73], v[20:21]
	v_pk_mul_f32 v[22:23], v[74:75], v[22:23]
	v_pk_mul_f32 v[36:37], v[38:39], v[4:5] op_sel_hi:[1,0]
	v_pk_mul_f32 v[38:39], v[40:41], v[4:5] op_sel_hi:[1,0]
	v_pk_fma_f32 v[18:19], v[18:19], v[20:21], v[50:51]
	v_pk_fma_f32 v[20:21], v[42:43], v[22:23], v[52:53]
	v_pk_mul_f32 v[0:1], v[0:1], v[4:5] op_sel_hi:[1,0]
	v_pk_mul_f32 v[2:3], v[2:3], v[4:5] op_sel_hi:[1,0]
	v_cvt_pk_bf16_f32 v18, v18, v19
	v_cvt_pk_bf16_f32 v19, v20, v21
	global_store_dwordx2 v[58:59], v[18:19], off
	v_pk_mul_f32 v[118:119], v[32:33], v[76:77]
	v_pk_add_f32 v[32:33], v[88:89], 1.0 op_sel_hi:[1,0]
	v_pk_mul_f32 v[120:121], v[34:35], v[78:79]
	v_pk_add_f32 v[34:35], v[90:91], 1.0 op_sel_hi:[1,0]
	v_pk_fma_f32 v[118:119], v[118:119], v[32:33], v[100:101]
	v_pk_fma_f32 v[120:121], v[120:121], v[34:35], v[102:103]
	v_pk_mul_f32 v[122:123], v[36:37], v[80:81]
	v_pk_add_f32 v[32:33], v[92:93], 1.0 op_sel_hi:[1,0]
	v_cvt_pk_bf16_f32 v118, v118, v119
	v_cvt_pk_bf16_f32 v119, v120, v121
	global_store_dwordx2 v[58:59], v[118:119], off offset:512
	v_pk_mul_f32 v[124:125], v[38:39], v[82:83]
	v_pk_add_f32 v[34:35], v[94:95], 1.0 op_sel_hi:[1,0]
	v_pk_fma_f32 v[122:123], v[122:123], v[32:33], v[104:105]
	v_pk_fma_f32 v[124:125], v[124:125], v[34:35], v[106:107]
	v_pk_mul_f32 v[0:1], v[0:1], v[84:85]
	v_pk_add_f32 v[32:33], v[96:97], 1.0 op_sel_hi:[1,0]
	v_cvt_pk_bf16_f32 v122, v122, v123
	v_cvt_pk_bf16_f32 v123, v124, v125
	global_store_dwordx2 v[58:59], v[122:123], off offset:1024
	v_pk_mul_f32 v[2:3], v[2:3], v[86:87]
	v_pk_add_f32 v[34:35], v[98:99], 1.0 op_sel_hi:[1,0]
	v_pk_fma_f32 v[0:1], v[0:1], v[32:33], v[108:109]
	v_pk_fma_f32 v[2:3], v[2:3], v[34:35], v[110:111]
	v_cmp_lt_i32_e32 vcc, s16, v24
	s_or_b64 s[8:9], vcc, s[8:9]
	v_cvt_pk_bf16_f32 v0, v0, v1
	v_cvt_pk_bf16_f32 v1, v2, v3
	global_store_dwordx2 v[58:59], v[0:1], off offset:1536
	s_andn2_b64 exec, exec, s[8:9]
	s_cbranch_execz .LBB0_58

.LBB0_476:
	v_add_co_u32_e32 v30, vcc, 0xfbc00000, v2
	v_and_b32_e32 v22, 0x7f8, v4
	s_nop 0
	v_addc_co_u32_e32 v31, vcc, -1, v3, vcc
	global_load_dwordx4 v[10:13], v[30:31], off nt
	global_load_dwordx4 v[14:17], v[2:3], off nt
	v_lshlrev_b32_e32 v26, 2, v22
	v_add_co_u32_e32 v18, vcc, 0xf7800000, v2
	s_mov_b32 s6, 0x800000
	s_nop 0
	v_addc_co_u32_e32 v19, vcc, -1, v3, vcc
	global_load_dwordx4 v[18:21], v[18:19], off nt
	v_lshl_add_u64 v[0:1], v[0:1], 0, s[2:3]
	v_lshl_add_u64 v[2:3], v[2:3], 0, s[8:9]
	v_lshl_add_u64 v[4:5], v[4:5], 0, s[12:13]
	s_waitcnt vmcnt(2)
	v_lshlrev_b32_e32 v22, 16, v13
	v_and_b32_e32 v23, 0xffff0000, v13
	s_waitcnt vmcnt(1)
	v_lshlrev_b32_e32 v24, 16, v17
	v_and_b32_e32 v25, 0xffff0000, v17
	v_pk_add_f32 v[32:33], v[22:23], v[24:25]
	v_lshlrev_b32_e32 v22, 16, v12
	v_and_b32_e32 v23, 0xffff0000, v12
	v_lshlrev_b32_e32 v12, 16, v16
	v_and_b32_e32 v13, 0xffff0000, v16
	v_pk_add_f32 v[12:13], v[22:23], v[12:13]
	v_mov_b32_e32 v22, v33
	v_mov_b32_e32 v23, v13
	v_mov_b32_e32 v16, v32
	v_mov_b32_e32 v17, v12
	v_pk_mul_f32 v[22:23], v[22:23], v[22:23]
	v_lshlrev_b32_e32 v36, 16, v11
	v_pk_fma_f32 v[16:17], v[16:17], v[16:17], v[22:23]
	global_load_dwordx4 v[22:25], v26, s[10:11] offset:16
	s_nop 0
	global_load_dwordx4 v[26:29], v26, s[10:11]
	v_and_b32_e32 v37, 0xffff0000, v11
	v_lshlrev_b32_e32 v38, 16, v15
	v_and_b32_e32 v39, 0xffff0000, v15
	v_lshlrev_b32_e32 v40, 16, v10
	v_and_b32_e32 v41, 0xffff0000, v10
	v_lshlrev_b32_e32 v10, 16, v14
	v_and_b32_e32 v11, 0xffff0000, v14
	v_pk_add_f32 v[36:37], v[36:37], v[38:39]
	v_pk_add_f32 v[10:11], v[40:41], v[10:11]
	v_mov_b32_e32 v41, v37
	v_mov_b32_e32 v40, v11
	v_mov_b32_e32 v14, v10
	v_mov_b32_e32 v15, v36
	v_pk_mul_f32 v[40:41], v[40:41], v[40:41]
	s_waitcnt vmcnt(2)
	v_lshlrev_b32_e32 v34, 16, v20
	v_pk_fma_f32 v[14:15], v[14:15], v[14:15], v[40:41]
	v_and_b32_e32 v35, 0xffff0000, v20
	v_add_f32_e32 v14, v14, v15
	v_add_f32_e32 v14, v17, v14
	v_add_f32_e32 v14, v16, v14
	v_lshlrev_b32_e32 v38, 16, v19
	v_and_b32_e32 v39, 0xffff0000, v19
	v_add_f32_dpp v14, v14, v14 quad_perm:[1,0,3,2] row_mask:0xf bank_mask:0xf
	v_lshlrev_b32_e32 v40, 16, v18
	v_and_b32_e32 v41, 0xffff0000, v18
	v_add_f32_dpp v14, v14, v14 quad_perm:[2,3,0,1] row_mask:0xf bank_mask:0xf
	v_lshlrev_b32_e32 v18, 16, v21
	v_and_b32_e32 v19, 0xffff0000, v21
	v_add_f32_dpp v14, v14, v14 row_half_mirror row_mask:0xf bank_mask:0xf
	s_nop 1
	v_add_f32_dpp v14, v14, v14 row_mirror row_mask:0xf bank_mask:0xf
	s_nop 1
	v_fmamk_f32 v14, v14, 0x3c000000, v205
	v_cmp_gt_f32_e32 vcc, s6, v14
	v_mul_f32_e32 v15, 0x4b800000, v14
	s_mov_b64 s[6:7], 0x43ffff
	v_cndmask_b32_e32 v14, v14, v15, vcc
	v_rsq_f32_e32 v14, v14
	s_nop 0
	v_mul_f32_e32 v15, 0x45800000, v14
	v_cndmask_b32_e32 v14, v14, v15, vcc
	v_pk_mul_f32 v[10:11], v[10:11], v[14:15] op_sel_hi:[1,0]
	v_pk_mul_f32 v[16:17], v[36:37], v[14:15] op_sel_hi:[1,0]
	v_pk_mul_f32 v[12:13], v[12:13], v[14:15] op_sel_hi:[1,0]
	v_pk_mul_f32 v[14:15], v[32:33], v[14:15] op_sel_hi:[1,0]
	v_cmp_lt_u64_e32 vcc, s[6:7], v[0:1]
	s_or_b64 s[14:15], vcc, s[14:15]
	s_waitcnt vmcnt(1)
	v_pk_mul_f32 v[12:13], v[22:23], v[12:13]
	s_waitcnt vmcnt(0)
	v_pk_mul_f32 v[10:11], v[26:27], v[10:11]
	v_pk_mul_f32 v[16:17], v[28:29], v[16:17]
	v_pk_mul_f32 v[14:15], v[24:25], v[14:15]
	v_pk_mul_f32 v[10:11], v[10:11], v[40:41]
	v_pk_mul_f32 v[16:17], v[16:17], v[38:39]
	v_pk_mul_f32 v[12:13], v[12:13], v[34:35]
	v_pk_mul_f32 v[14:15], v[14:15], v[18:19]
	v_cvt_pk_bf16_f32 v10, v10, v11
	v_cvt_pk_bf16_f32 v11, v16, v17
	v_cvt_pk_bf16_f32 v12, v12, v13
	v_cvt_pk_bf16_f32 v13, v14, v15
	global_store_dwordx4 v[30:31], v[10:13], off
	s_andn2_b64 exec, exec, s[14:15]
	s_cbranch_execnz .LBB0_476

.LBB0_620:
	s_or_b64 exec, exec, s[4:5]
	v_lshlrev_b64 v[0:1], v4, v[0:1]
	v_lshl_add_u64 v[0:1], v[6:7], 0, v[0:1]
	v_lshlrev_b64 v[2:3], 12, v[2:3]
	v_lshl_add_u64 v[0:1], v[0:1], 0, v[2:3]
	v_lshl_add_u64 v[64:65], v[0:1], 0, v[26:27]
	global_load_dwordx4 v[12:15], v[64:65], off nt
	global_load_dwordx4 v[8:11], v[64:65], off offset:1024 nt
	global_load_dwordx4 v[4:7], v[64:65], off offset:2048 nt
	global_load_dwordx4 v[0:3], v[64:65], off offset:3072 nt
	v_ashrrev_i32_e32 v40, 13, v40
	v_lshl_add_u64 v[38:39], s[28:29], 0, v[38:39]
	s_mov_b64 s[4:5], 0x1000
	v_lshl_add_u64 v[66:67], v[38:39], 0, s[4:5]
	v_lshl_add_u64 v[38:39], v[38:39], 0, v[26:27]
	v_lshl_add_u64 v[68:69], v[66:67], 0, v[26:27]
	global_load_dwordx4 v[72:75], v[38:39], off
	global_load_dwordx4 v[88:91], v[68:69], off
	v_lshl_add_u64 v[68:69], v[66:67], 0, v[32:33]
	global_load_dwordx4 v[76:79], v[38:39], off offset:1024
	global_load_dwordx4 v[92:95], v[68:69], off
	v_lshl_add_u64 v[68:69], v[66:67], 0, v[34:35]
	global_load_dwordx4 v[80:83], v[38:39], off offset:2048
	global_load_dwordx4 v[96:99], v[68:69], off
	v_lshl_add_u64 v[68:69], v[66:67], 0, v[36:37]
	global_load_dwordx4 v[84:87], v[38:39], off offset:3072
	global_load_dwordx4 v[100:103], v[68:69], off
	s_mov_b32 s4, 0x800000
	s_waitcnt vmcnt(11)
	v_mov_b32_e32 v120, v13
	s_waitcnt vmcnt(10)
	v_mov_b32_e32 v121, v9
	v_mov_b32_e32 v122, v12
	v_mov_b32_e32 v123, v8
	v_pk_mul_f32 v[120:121], v[120:121], v[120:121]
	s_nop 0
	v_pk_fma_f32 v[122:123], v[122:123], v[122:123], v[120:121]
	v_mov_b32_e32 v120, v14
	v_mov_b32_e32 v121, v10
	v_pk_fma_f32 v[122:123], v[120:121], v[120:121], v[122:123]
	v_mov_b32_e32 v120, v15
	v_mov_b32_e32 v121, v11
	v_pk_fma_f32 v[50:51], v[120:121], v[120:121], v[122:123]
	s_nop 0
	v_add_f32_e32 v16, v50, v51
	s_waitcnt vmcnt(9)
	v_mov_b32_e32 v54, v5
	s_waitcnt vmcnt(8)
	v_mov_b32_e32 v55, v1
	v_mov_b32_e32 v52, v4
	v_mov_b32_e32 v53, v0
	v_pk_mul_f32 v[54:55], v[54:55], v[54:55]
	s_nop 0
	v_pk_fma_f32 v[52:53], v[52:53], v[52:53], v[54:55]
	v_mov_b32_e32 v54, v6
	v_mov_b32_e32 v55, v2
	v_pk_fma_f32 v[52:53], v[54:55], v[54:55], v[52:53]
	v_mov_b32_e32 v54, v7
	v_mov_b32_e32 v55, v3
	v_pk_fma_f32 v[52:53], v[54:55], v[54:55], v[52:53]
	s_nop 0
	v_add_f32_e32 v16, v16, v52
	v_add_f32_e32 v16, v16, v53
	s_nop 1
	v_add_f32_dpp v16, v16, v16 quad_perm:[1,0,3,2] row_mask:0xf bank_mask:0xf
	s_nop 1
	v_add_f32_dpp v16, v16, v16 quad_perm:[2,3,0,1] row_mask:0xf bank_mask:0xf
	s_nop 1
	v_add_f32_dpp v16, v16, v16 row_half_mirror row_mask:0xf bank_mask:0xf
	s_nop 1
	v_add_f32_dpp v16, v16, v16 row_mirror row_mask:0xf bank_mask:0xf
	v_mov_b32_e32 v70, v16
	v_mov_b32_e32 v71, v16
	s_nop 1
	v_permlane16_swap_b32 v70, v71
	s_nop 1
	v_add_f32_e32 v16, v70, v71
	v_mov_b32_e32 v70, v16
	v_mov_b32_e32 v71, v16
	s_nop 1
	v_permlane32_swap_b32 v70, v71
	s_nop 1
	v_add_f32_e32 v16, v70, v71
	v_fmamk_f32 v16, v16, 0x3a800000, v49
	v_cmp_gt_f32_e32 vcc, s4, v16
	v_mul_f32_e32 v50, 0x4b800000, v16
	s_mov_b32 s4, 0x2200000
	v_cndmask_b32_e32 v16, v16, v50, vcc
	v_rsq_f32_e32 v16, v16
	s_nop 0
	v_mul_f32_e32 v50, 0x45800000, v16
	v_cndmask_b32_e32 v16, v16, v50, vcc
	v_add_u32_e32 v50, v40, v41
	v_mad_i64_i32 v[40:41], s[4:5], v50, s4, v[28:29]
	v_mul_i32_i24_e32 v50, 0x4400, v50
	v_sub_u32_e32 v50, v42, v50
	v_ashrrev_i32_e32 v51, 31, v50
	v_lshlrev_b64 v[50:51], 11, v[50:51]
	v_lshl_add_u64 v[62:63], v[40:41], 0, v[50:51]
	s_waitcnt vmcnt(0)
	v_pk_mul_f32 v[12:13], v[12:13], v[16:17] op_sel_hi:[1,0]
	v_pk_mul_f32 v[14:15], v[14:15], v[16:17] op_sel_hi:[1,0]
	v_pk_mul_f32 v[8:9], v[8:9], v[16:17] op_sel_hi:[1,0]
	v_pk_mul_f32 v[10:11], v[10:11], v[16:17] op_sel_hi:[1,0]
	v_pk_mul_f32 v[4:5], v[4:5], v[16:17] op_sel_hi:[1,0]
	v_pk_mul_f32 v[6:7], v[6:7], v[16:17] op_sel_hi:[1,0]
	v_pk_mul_f32 v[0:1], v[0:1], v[16:17] op_sel_hi:[1,0]
	v_pk_mul_f32 v[2:3], v[2:3], v[16:17] op_sel_hi:[1,0]
	v_lshl_add_u64 v[126:127], v[62:63], 0, v[30:31]
	v_add_u32_e32 v42, s6, v42
	v_pk_mul_f32 v[12:13], v[104:105], v[12:13]
	v_pk_mul_f32 v[14:15], v[106:107], v[14:15]
	v_pk_add_f32 v[50:51], v[88:89], 1.0 op_sel_hi:[1,0]
	v_pk_add_f32 v[52:53], v[90:91], 1.0 op_sel_hi:[1,0]
	v_pk_mul_f32 v[8:9], v[8:9], v[108:109]
	v_pk_fma_f32 v[12:13], v[50:51], v[12:13], v[72:73]
	v_pk_fma_f32 v[14:15], v[52:53], v[14:15], v[74:75]
	v_pk_mul_f32 v[10:11], v[10:11], v[110:111]
	v_pk_add_f32 v[50:51], v[92:93], 1.0 op_sel_hi:[1,0]
	v_cvt_pk_bf16_f32 v120, v12, v13
	v_cvt_pk_bf16_f32 v121, v14, v15
	global_store_dwordx2 v[126:127], v[120:121], off
	v_pk_add_f32 v[52:53], v[94:95], 1.0 op_sel_hi:[1,0]
	v_pk_fma_f32 v[8:9], v[8:9], v[50:51], v[76:77]
	v_pk_mul_f32 v[4:5], v[4:5], v[112:113]
	v_pk_fma_f32 v[10:11], v[10:11], v[52:53], v[78:79]
	v_pk_mul_f32 v[6:7], v[6:7], v[114:115]
	v_pk_add_f32 v[50:51], v[96:97], 1.0 op_sel_hi:[1,0]
	v_cvt_pk_bf16_f32 v122, v8, v9
	v_cvt_pk_bf16_f32 v123, v10, v11
	global_store_dwordx2 v[126:127], v[122:123], off offset:512
	v_pk_add_f32 v[52:53], v[98:99], 1.0 op_sel_hi:[1,0]
	v_pk_fma_f32 v[4:5], v[4:5], v[50:51], v[80:81]
	v_pk_mul_f32 v[0:1], v[0:1], v[116:117]
	v_pk_fma_f32 v[6:7], v[6:7], v[52:53], v[82:83]
	v_pk_mul_f32 v[2:3], v[2:3], v[118:119]
	v_pk_add_f32 v[50:51], v[100:101], 1.0 op_sel_hi:[1,0]
	v_cvt_pk_bf16_f32 v124, v4, v5
	v_cvt_pk_bf16_f32 v125, v6, v7
	global_store_dwordx2 v[126:127], v[124:125], off offset:1024
	v_pk_add_f32 v[52:53], v[102:103], 1.0 op_sel_hi:[1,0]
	v_pk_fma_f32 v[0:1], v[0:1], v[50:51], v[84:85]
	s_mov_b32 s4, 0x87ff
	v_cmp_lt_i32_e32 vcc, s4, v42
	v_pk_fma_f32 v[2:3], v[2:3], v[52:53], v[86:87]
	s_or_b64 s[2:3], vcc, s[2:3]
	v_cvt_pk_bf16_f32 v0, v0, v1
	s_nop 0
	v_cvt_pk_bf16_f32 v1, v2, v3
	global_store_dwordx2 v[126:127], v[0:1], off offset:1536
	s_andn2_b64 exec, exec, s[2:3]
	s_cbranch_execz .LBB0_625

.LBB0_1290:
	v_ashrrev_i32_e32 v1, 31, v0
	v_lshlrev_b64 v[14:15], 12, v[0:1]
	v_lshl_add_u64 v[34:35], v[4:5], 0, v[14:15]
	global_load_dwordx4 v[14:17], v[34:35], off
	global_load_dwordx4 v[18:21], v[34:35], off offset:1024
	global_load_dwordx4 v[22:25], v[34:35], off offset:2048
	global_load_dwordx4 v[26:29], v[34:35], off offset:3072
	v_add_u32_e32 v0, s4, v0
	s_waitcnt vmcnt(3)
	v_mov_b32_e32 v38, v15
	s_waitcnt vmcnt(2)
	v_mov_b32_e32 v39, v19
	v_mov_b32_e32 v36, v14
	v_mov_b32_e32 v37, v18
	s_waitcnt vmcnt(1)
	v_mov_b32_e32 v46, v23
	s_waitcnt vmcnt(0)
	v_mov_b32_e32 v47, v27
	v_pk_mul_f32 v[38:39], v[38:39], v[38:39]
	v_mov_b32_e32 v40, v16
	v_mov_b32_e32 v41, v20
	v_mov_b32_e32 v44, v22
	v_mov_b32_e32 v45, v26
	v_pk_mul_f32 v[46:47], v[46:47], v[46:47]
	v_pk_fma_f32 v[36:37], v[36:37], v[36:37], v[38:39]
	v_mov_b32_e32 v42, v17
	v_mov_b32_e32 v43, v21
	v_mov_b32_e32 v48, v24
	v_mov_b32_e32 v49, v28
	v_pk_fma_f32 v[38:39], v[44:45], v[44:45], v[46:47]
	v_pk_fma_f32 v[36:37], v[40:41], v[40:41], v[36:37]
	v_mov_b32_e32 v50, v25
	v_mov_b32_e32 v51, v29
	v_pk_fma_f32 v[38:39], v[48:49], v[48:49], v[38:39]
	v_pk_fma_f32 v[36:37], v[42:43], v[42:43], v[36:37]
	v_pk_fma_f32 v[38:39], v[50:51], v[50:51], v[38:39]
	v_add_f32_e32 v1, v36, v37
	v_add_f32_e32 v1, v1, v38
	v_add_f32_e32 v1, v1, v39
	s_nop 1
	v_add_f32_dpp v1, v1, v1 quad_perm:[1,0,3,2] row_mask:0xf bank_mask:0xf
	s_nop 1
	v_add_f32_dpp v1, v1, v1 quad_perm:[2,3,0,1] row_mask:0xf bank_mask:0xf
	s_nop 1
	v_add_f32_dpp v1, v1, v1 row_half_mirror row_mask:0xf bank_mask:0xf
	s_nop 1
	v_add_f32_dpp v1, v1, v1 row_mirror row_mask:0xf bank_mask:0xf
	v_mov_b32_e32 v68, v1
	v_mov_b32_e32 v69, v1
	s_nop 1
	v_permlane16_swap_b32 v68, v69
	s_nop 1
	v_add_f32_e32 v1, v68, v69
	v_mov_b32_e32 v68, v1
	v_mov_b32_e32 v69, v1
	s_nop 1
	v_permlane32_swap_b32 v68, v69
	s_nop 1
	v_add_f32_e32 v1, v68, v69
	v_fmamk_f32 v1, v1, 0x3a800000, v12
	v_mul_f32_e32 v13, 0x4b800000, v1
	v_cmp_gt_f32_e32 vcc, s5, v1
	s_nop 1
	v_cndmask_b32_e32 v1, v1, v13, vcc
	v_rsq_f32_e32 v1, v1
	s_nop 0
	v_mul_f32_e32 v13, 0x45800000, v1
	v_cndmask_b32_e32 v36, v1, v13, vcc
	v_pk_mul_f32 v[14:15], v[14:15], v[36:37] op_sel_hi:[1,0]
	v_pk_mul_f32 v[16:17], v[16:17], v[36:37] op_sel_hi:[1,0]
	v_pk_mul_f32 v[18:19], v[18:19], v[36:37] op_sel_hi:[1,0]
	v_pk_mul_f32 v[20:21], v[20:21], v[36:37] op_sel_hi:[1,0]
	v_pk_mul_f32 v[22:23], v[22:23], v[36:37] op_sel_hi:[1,0]
	v_pk_mul_f32 v[24:25], v[24:25], v[36:37] op_sel_hi:[1,0]
	v_pk_mul_f32 v[26:27], v[26:27], v[36:37] op_sel_hi:[1,0]
	v_pk_mul_f32 v[28:29], v[28:29], v[36:37] op_sel_hi:[1,0]
	v_pk_mul_f32 v[14:15], v[52:53], v[14:15]
	v_pk_mul_f32 v[16:17], v[54:55], v[16:17]
	v_pk_mul_f32 v[18:19], v[56:57], v[18:19]
	v_pk_mul_f32 v[20:21], v[58:59], v[20:21]
	v_pk_mul_f32 v[22:23], v[22:23], v[60:61]
	v_pk_mul_f32 v[24:25], v[24:25], v[62:63]
	v_pk_mul_f32 v[26:27], v[26:27], v[64:65]
	v_pk_mul_f32 v[28:29], v[28:29], v[66:67]
	v_cmp_lt_i32_e32 vcc, s6, v0
	s_or_b64 s[2:3], vcc, s[2:3]
	global_store_dwordx4 v[34:35], v[14:17], off
	global_store_dwordx4 v[34:35], v[18:21], off offset:1024
	global_store_dwordx4 v[34:35], v[22:25], off offset:2048
	global_store_dwordx4 v[34:35], v[26:29], off offset:3072
	s_andn2_b64 exec, exec, s[2:3]
	s_cbranch_execnz .LBB0_1290
